# RSTD GEMM phases: phase-entry rstd-table loads issued after the first 8 tile DMAs instead of before (latencies overlap)
# speedup vs baseline: 1.0042x; 1.0004x over previous
; #define PG8_STAGE(bufoff, gbase, voff) do { _Pragma("unroll") for (int _i = 0; _i < 2; ++_i) \
;         __builtin_amdgcn_global_load_lds((const unsigned*)((const char*)(gbase) + (voff)[_i]), (PG8_LAS unsigned*)(lds + (bufoff) + ldsw + _i * 8192), 16, 0, 0); } while (0)
; #define PG8_BAR __builtin_amdgcn_s_barrier()
; template <class Epi, class Sched, bool ALIGN_EPI = false, bool SP2 = false, bool TA = true>
; __device__ __forceinline__ void gemm_phase(PG8_LAS unsigned char* lds, const Gemm g, const Sched& S, const Epi& E) {
;     ...
;     PG8_RTAB(cur, 0);
;     ...
;         PG8_STAGE(PG8_SB(0, 0), cB, voffB); PG8_STAGE(PG8_SA(0, 0), cA, voffA); PG8_STAGE(PG8_SB(0, 1), cB + hstep, voffB); PG8_STAGE(PG8_SA(0, 1), cA + hstep, voffA);
;         if (wr == 1) PG8_BAR;
.LBB0_474:
	s_ashr_i32 s2, s4, 3
	s_add_i32 s2, s6, s2
	s_ashr_i32 s3, s2, 31
	s_lshr_b32 s3, s3, 26
	s_add_i32 s3, s2, s3
	s_ashr_i32 s4, s3, 6
	s_andn2_b32 s3, s3, 63
	s_sub_i32 s2, s2, s3
	s_bfe_i32 s3, s2, 0x80000
	s_bfe_u32 s3, s3, 0x3000c
	s_add_i32 s3, s2, s3
	s_bfe_i32 s5, s3, 0x80000
	s_and_b32 s3, s3, 0xf8
	s_sub_i32 s2, s2, s3
	s_lshl_b32 s4, s4, 3
	s_sext_i32_i8 s2, s2
	s_sext_i32_i16 s5, s5
	s_add_i32 s74, s4, s2
	s_movk_i32 s2, 0x100
	s_lshr_b32 s23, s5, 3
	v_cmp_gt_u32_e64 s[2:3], s2, v208
	v_mov_b32_e32 v0, s23
	s_add_u32 s90, s28, 0x800000
	v_readfirstlane_b32 s84, v0
	s_mov_b32 s85, 0
	s_addc_u32 s91, s29, 0
	s_lshr_b32 s4, s22, 6
	s_ashr_i32 s75, s74, 31
	s_bfe_i64 s[6:7], s[84:85], 0x80000
	s_lshr_b32 s5, s22, 8
	s_lshl_b32 s93, s4, 10
	s_lshl_b64 s[12:13], s[74:75], 19
	s_lshl_b64 s[6:7], s[6:7], 19
	s_add_u32 s88, s90, s6
	v_lshlrev_b32_e32 v144, 4, v208
	v_mov_b32_e32 v145, 0
	s_addc_u32 s89, s91, s7
	s_add_i32 s84, s93, 0
	s_add_i32 m0, s84, 0x10000
	v_lshl_add_u64 v[0:1], s[88:89], 0, v[144:145]
	s_mov_b64 s[6:7], 0x2000
	global_load_lds_dwordx4 v144, s[88:89]
	v_lshl_add_u64 v[2:3], v[0:1], 0, s[6:7]
	s_add_i32 m0, s84, 0x12000
	s_mov_b64 s[8:9], 0x40000
	global_load_lds_dwordx4 v[2:3], off
	s_add_i32 m0, s84, 0x14000
	v_lshl_add_u64 v[2:3], v[0:1], 0, s[8:9]
	global_load_lds_dwordx4 v[2:3], off
	s_add_i32 m0, s84, 0x16000
	s_mov_b64 s[10:11], 0x42000
	s_add_u32 s86, s34, s12
	v_lshl_add_u64 v[2:3], v[0:1], 0, s[10:11]
	s_addc_u32 s87, s35, s13
	global_load_lds_dwordx4 v[2:3], off
	v_lshl_add_u64 v[2:3], s[86:87], 0, v[144:145]
	s_mov_b32 m0, s84
	s_add_i32 s92, s84, 0x2000
	global_load_lds_dwordx4 v144, s[86:87]
	v_lshl_add_u64 v[4:5], v[2:3], 0, s[6:7]
	s_mov_b32 m0, s92
	s_add_i32 s94, s84, 0x4000
	global_load_lds_dwordx4 v[4:5], off
	v_lshl_add_u64 v[4:5], v[2:3], 0, s[8:9]
	s_mov_b32 m0, s94
	s_add_i32 s18, s84, 0x6000
	global_load_lds_dwordx4 v[4:5], off
	v_lshl_add_u64 v[4:5], v[2:3], 0, s[10:11]
	s_mov_b32 m0, s18
	s_cmp_eq_u32 s5, 1
	global_load_lds_dwordx4 v[4:5], off
	s_cselect_b64 s[12:13], -1, 0
	s_and_saveexec_b64 s[98:99], s[2:3]
	s_cbranch_execz .LBB0_476
	v_lshl_or_b32 v224, s74, 8, v208
	v_ashrrev_i32_e32 v225, 31, v224
	v_lshlrev_b64 v[224:225], 6, v[224:225]
	v_lshl_add_u64 v[236:237], s[24:25], 0, v[224:225]
	global_load_dwordx4 v[224:227], v[236:237], off
	global_load_dwordx4 v[228:231], v[236:237], off offset:16
	global_load_dwordx4 v[232:235], v[236:237], off offset:32
	s_nop 0
	global_load_dwordx4 v[236:239], v[236:237], off offset:48
	s_waitcnt vmcnt(2)
	v_pk_add_f32 v[226:227], v[226:227], v[230:231]
	v_pk_add_f32 v[224:225], v[224:225], v[228:229]
	s_waitcnt vmcnt(0)
	v_pk_add_f32 v[228:229], v[234:235], v[238:239]
	v_pk_add_f32 v[230:231], v[232:233], v[236:237]
	v_pk_add_f32 v[226:227], v[226:227], v[228:229]
	v_pk_add_f32 v[224:225], v[224:225], v[230:231]
	s_nop 0
	v_pk_mov_b32 v[228:229], v[224:225], v[226:227] op_sel:[1,0]
	v_mov_b32_e32 v225, v227
	v_pk_add_f32 v[224:225], v[228:229], v[224:225]
	s_nop 0
	v_add_f32_e32 v224, v224, v225
	v_mov_b32_e32 v225, 0x358637bd
	v_fmac_f32_e32 v225, 0x3a800000, v224
	v_rsq_f32_e32 v224, v225
	v_lshl_add_u32 v225, v208, 2, 0
	v_add_u32_e32 v225, 0x20400, v225
	ds_write_b32 v225, v224
.LBB0_476:
	s_or_b64 exec, exec, s[98:99]
	s_cmp_lg_u32 s5, 1
	s_cbranch_scc1 .LBB0_478
	s_barrier

; #define PG8_STAGE(bufoff, gbase, voff) do { _Pragma("unroll") for (int _i = 0; _i < 2; ++_i) \
;         __builtin_amdgcn_global_load_lds((const unsigned*)((const char*)(gbase) + (voff)[_i]), (PG8_LAS unsigned*)(lds + (bufoff) + ldsw + _i * 8192), 16, 0, 0); } while (0)
; #define PG8_BAR __builtin_amdgcn_s_barrier()
; template <class Epi, class Sched, bool ALIGN_EPI = false, bool SP2 = false, bool TA = true>
; __device__ __forceinline__ void gemm_phase(PG8_LAS unsigned char* lds, const Gemm g, const Sched& S, const Epi& E) {
;     ...
;     PG8_RTAB(cur, 0);
;     ...
;         PG8_STAGE(PG8_SB(0, 0), cB, voffB); PG8_STAGE(PG8_SA(0, 0), cA, voffA); PG8_STAGE(PG8_SB(0, 1), cB + hstep, voffB); PG8_STAGE(PG8_SA(0, 1), cA + hstep, voffA);
;         if (wr == 1) PG8_BAR;
.LBB0_778:
	s_cmp_lt_i32 s36, 5
	s_cselect_b64 s[2:3], -1, 0
	s_and_b64 s[0:1], s[2:3], s[0:1]
	s_andn2_b64 vcc, exec, s[0:1]
	s_cbranch_vccnz .LBB0_799
	s_cmpk_gt_i32 s20, 0xaff
	v_readfirstlane_b32 s41, v208
	s_cbranch_scc1 .LBB0_799
	s_ashr_i32 s18, s20, 31
	s_lshr_b32 s2, s18, 29
	s_add_i32 s2, s20, s2
	s_ashr_i32 s3, s2, 3
	s_and_b32 s2, s2, -8
	s_sub_i32 s2, s20, s2
	s_cmp_lt_i32 s2, 0
	s_movk_i32 s4, 0x161
	s_cselect_b32 s4, s4, 0x160
	s_mul_i32 s2, s2, s4
	s_add_i32 s2, s2, s3
	s_mul_hi_i32 s3, s2, 0x2e8ba2e9
	s_lshr_b32 s4, s3, 31
	s_ashr_i32 s3, s3, 5
	s_add_i32 s3, s3, s4
	s_lshl_b32 s4, s3, 3
	s_mulk_i32 s3, 0xb0
	s_sub_i32 s2, s2, s3
	s_sext_i32_i16 s3, s2
	s_bfe_u32 s3, s3, 0x3001c
	s_add_i32 s3, s2, s3
	s_sext_i32_i16 s5, s3
	s_and_b32 s3, s3, 0xfff8
	s_sub_i32 s2, s2, s3
	s_sext_i32_i16 s2, s2
	s_add_i32 s60, s4, s2
	s_movk_i32 s2, 0x100
	s_lshr_b32 s6, s5, 3
	v_cmp_gt_u32_e64 s[2:3], s2, v208
	s_sext_i32_i16 s68, s6
	s_add_u32 s19, s28, 0x1600000
	s_addc_u32 s21, s29, 0
	s_lshr_b32 s5, s41, 6
	s_ashr_i32 s61, s60, 31
	s_ashr_i32 s69, s68, 31
	s_lshr_b32 s4, s41, 8
	s_lshl_b32 s22, s5, 10
	s_lshl_b64 s[12:13], s[60:61], 19
	s_lshl_b64 s[6:7], s[68:69], 19
	s_add_u32 s72, s19, s6
	v_mov_b32_e32 v131, 0
	v_lshlrev_b32_e32 v128, 4, v208
	s_addc_u32 s73, s21, s7
	s_add_i32 s23, s22, 0
	v_mov_b32_e32 v129, v131
	s_add_i32 m0, s23, 0x10000
	s_waitcnt lgkmcnt(0)
	v_lshl_add_u64 v[0:1], s[72:73], 0, v[128:129]
	s_mov_b64 s[6:7], 0x2000
	global_load_lds_dwordx4 v128, s[72:73]
	v_lshl_add_u64 v[2:3], v[0:1], 0, s[6:7]
	s_add_i32 m0, s23, 0x12000
	s_mov_b64 s[8:9], 0x40000
	global_load_lds_dwordx4 v[2:3], off
	s_add_i32 m0, s23, 0x14000
	v_lshl_add_u64 v[2:3], v[0:1], 0, s[8:9]
	global_load_lds_dwordx4 v[2:3], off
	s_add_i32 m0, s23, 0x16000
	s_mov_b64 s[10:11], 0x42000
	s_add_u32 s70, s34, s12
	v_lshl_add_u64 v[2:3], v[0:1], 0, s[10:11]
	s_addc_u32 s71, s35, s13
	global_load_lds_dwordx4 v[2:3], off
	v_lshl_add_u64 v[2:3], s[70:71], 0, v[128:129]
	s_mov_b32 m0, s23
	s_add_i32 s30, s23, 0x2000
	global_load_lds_dwordx4 v128, s[70:71]
	v_lshl_add_u64 v[4:5], v[2:3], 0, s[6:7]
	s_mov_b32 m0, s30
	s_add_i32 s31, s23, 0x4000
	global_load_lds_dwordx4 v[4:5], off
	v_lshl_add_u64 v[4:5], v[2:3], 0, s[8:9]
	s_mov_b32 m0, s31
	s_add_i32 s33, s23, 0x6000
	global_load_lds_dwordx4 v[4:5], off
	v_lshl_add_u64 v[4:5], v[2:3], 0, s[10:11]
	s_mov_b32 m0, s33
	s_cmp_eq_u32 s4, 1
	global_load_lds_dwordx4 v[4:5], off
	s_cselect_b64 s[12:13], -1, 0
	s_and_saveexec_b64 s[98:99], s[2:3]
	s_cbranch_execz .LBB0_782
	v_lshl_or_b32 v224, s60, 8, v208
	s_waitcnt lgkmcnt(0)
	v_ashrrev_i32_e32 v225, 31, v224
	v_lshlrev_b64 v[224:225], 6, v[224:225]
	v_lshl_add_u64 v[240:241], s[24:25], 0, v[224:225]
	global_load_dwordx4 v[224:227], v[240:241], off
	global_load_dwordx4 v[228:231], v[240:241], off offset:16
	global_load_dwordx4 v[232:235], v[240:241], off offset:32
	global_load_dwordx4 v[236:239], v[240:241], off offset:48
	s_waitcnt vmcnt(2)
	v_pk_add_f32 v[226:227], v[226:227], v[230:231]
	v_pk_add_f32 v[224:225], v[224:225], v[228:229]
	s_waitcnt vmcnt(0)
	v_pk_add_f32 v[228:229], v[234:235], v[238:239]
	v_pk_add_f32 v[230:231], v[232:233], v[236:237]
	v_pk_add_f32 v[226:227], v[226:227], v[228:229]
	v_pk_add_f32 v[224:225], v[224:225], v[230:231]
	s_nop 0
	v_pk_mov_b32 v[228:229], v[224:225], v[226:227] op_sel:[1,0]
	v_mov_b32_e32 v225, v227
	v_pk_add_f32 v[224:225], v[228:229], v[224:225]
	s_nop 0
	v_add_f32_e32 v224, v224, v225
	v_mov_b32_e32 v225, 0x358637bd
	v_fmac_f32_e32 v225, 0x3a800000, v224
	v_rsq_f32_e32 v224, v225
	v_lshl_add_u32 v225, v208, 2, 0
	v_add_u32_e32 v225, 0x20400, v225
	ds_write_b32 v225, v224
.LBB0_782:
	s_or_b64 exec, exec, s[98:99]
	s_cmp_lg_u32 s4, 1
	s_cbranch_scc1 .LBB0_784
	s_barrier

; #define PG8_STAGE(bufoff, gbase, voff) do { _Pragma("unroll") for (int _i = 0; _i < 2; ++_i) \
;         __builtin_amdgcn_global_load_lds((const unsigned*)((const char*)(gbase) + (voff)[_i]), (PG8_LAS unsigned*)(lds + (bufoff) + ldsw + _i * 8192), 16, 0, 0); } while (0)
; #define PG8_BAR __builtin_amdgcn_s_barrier()
; template <class Epi, class Sched, bool ALIGN_EPI = false, bool SP2 = false, bool TA = true>
; __device__ __forceinline__ void gemm_phase(PG8_LAS unsigned char* lds, const Gemm g, const Sched& S, const Epi& E) {
;     ...
;     PG8_RTAB(cur, 0);
;     ...
;         PG8_STAGE(PG8_SB(0, 0), cB, voffB); PG8_STAGE(PG8_SA(0, 0), cA, voffA); PG8_STAGE(PG8_SB(0, 1), cB + hstep, voffB); PG8_STAGE(PG8_SA(0, 1), cA + hstep, voffA);
;         if (wr == 1) PG8_BAR;
.LBB0_985:
	s_andn2_b64 vcc, exec, s[2:3]
	s_cbranch_vccnz .LBB0_1025
	s_movk_i32 s2, 0x100
	v_cmp_gt_u32_e64 s[2:3], s2, v208
	s_add_u32 s33, s28, 0x3800000
	s_addc_u32 s93, s29, 0
	s_lshr_b32 s5, s6, 6
	s_ashr_i32 s75, s74, 31
	s_ashr_i32 s47, s46, 31
	s_lshr_b32 s4, s6, 8
	s_lshl_b32 s94, s5, 10
	s_lshl_b64 s[18:19], s[74:75], 19
	s_lshl_b64 s[12:13], s[46:47], 19
	s_add_u32 s78, s33, s12
	v_mov_b32_e32 v147, 0
	v_lshlrev_b32_e32 v144, 4, v208
	s_addc_u32 s79, s93, s13
	s_add_i32 s95, s94, 0
	v_mov_b32_e32 v145, v147
	s_add_i32 m0, s95, 0x10000
	s_waitcnt lgkmcnt(0)
	v_lshl_add_u64 v[0:1], s[78:79], 0, v[144:145]
	s_mov_b64 s[12:13], 0x2000
	global_load_lds_dwordx4 v144, s[78:79]
	v_lshl_add_u64 v[2:3], v[0:1], 0, s[12:13]
	s_add_i32 m0, s95, 0x12000
	s_mov_b64 s[14:15], 0x40000
	global_load_lds_dwordx4 v[2:3], off
	s_add_i32 m0, s95, 0x14000
	v_lshl_add_u64 v[2:3], v[0:1], 0, s[14:15]
	global_load_lds_dwordx4 v[2:3], off
	s_add_i32 m0, s95, 0x16000
	s_mov_b64 s[16:17], 0x42000
	s_add_u32 s76, s34, s18
	v_lshl_add_u64 v[2:3], v[0:1], 0, s[16:17]
	s_addc_u32 s77, s35, s19
	global_load_lds_dwordx4 v[2:3], off
	v_lshl_add_u64 v[2:3], s[76:77], 0, v[144:145]
	s_mov_b32 m0, s95
	s_add_i32 s96, s95, 0x2000
	global_load_lds_dwordx4 v144, s[76:77]
	v_lshl_add_u64 v[4:5], v[2:3], 0, s[12:13]
	s_mov_b32 m0, s96
	s_add_i32 s97, s95, 0x4000
	global_load_lds_dwordx4 v[4:5], off
	v_lshl_add_u64 v[4:5], v[2:3], 0, s[14:15]
	s_mov_b32 m0, s97
	s_add_i32 s92, s95, 0x6000
	global_load_lds_dwordx4 v[4:5], off
	v_lshl_add_u64 v[4:5], v[2:3], 0, s[16:17]
	s_mov_b32 m0, s92
	s_cmp_eq_u32 s4, 1
	global_load_lds_dwordx4 v[4:5], off
	s_cselect_b64 s[44:45], -1, 0
	s_and_saveexec_b64 s[98:99], s[2:3]
	s_cbranch_execz .LBB0_988
	v_lshl_or_b32 v224, s74, 8, v208
	s_waitcnt lgkmcnt(0)
	v_ashrrev_i32_e32 v225, 31, v224
	v_lshlrev_b64 v[224:225], 6, v[224:225]
	v_lshl_add_u64 v[240:241], s[24:25], 0, v[224:225]
	global_load_dwordx4 v[224:227], v[240:241], off
	global_load_dwordx4 v[228:231], v[240:241], off offset:16
	global_load_dwordx4 v[232:235], v[240:241], off offset:32
	global_load_dwordx4 v[236:239], v[240:241], off offset:48
	s_waitcnt vmcnt(0)
	v_pk_add_f32 v[226:227], v[226:227], v[230:231]
	v_pk_add_f32 v[224:225], v[224:225], v[228:229]
	v_pk_add_f32 v[228:229], v[234:235], v[238:239]
	v_pk_add_f32 v[230:231], v[232:233], v[236:237]
	v_pk_add_f32 v[226:227], v[226:227], v[228:229]
	v_pk_add_f32 v[224:225], v[224:225], v[230:231]
	s_nop 0
	v_pk_mov_b32 v[228:229], v[224:225], v[226:227] op_sel:[1,0]
	v_mov_b32_e32 v225, v227
	v_pk_add_f32 v[224:225], v[228:229], v[224:225]
	s_nop 0
	v_add_f32_e32 v224, v224, v225
	v_mov_b32_e32 v225, 0x358637bd
	v_fmac_f32_e32 v225, 0x3a800000, v224
	v_rsq_f32_e32 v224, v225
	v_lshl_add_u32 v225, v208, 2, 0
	v_add_u32_e32 v225, 0x20400, v225
	ds_write_b32 v225, v224
.LBB0_988:
	s_or_b64 exec, exec, s[98:99]
	s_cmp_lg_u32 s4, 1
	s_mov_b32 s47, 0
	s_cbranch_scc1 .LBB0_990
	s_barrier

; #define PG8_STAGE(bufoff, gbase, voff) do { _Pragma("unroll") for (int _i = 0; _i < 2; ++_i) \
;         __builtin_amdgcn_global_load_lds((const unsigned*)((const char*)(gbase) + (voff)[_i]), (PG8_LAS unsigned*)(lds + (bufoff) + ldsw + _i * 8192), 16, 0, 0); } while (0)
; #define PG8_BAR __builtin_amdgcn_s_barrier()
; template <class Epi, class Sched, bool ALIGN_EPI = false, bool SP2 = false, bool TA = true>
; __device__ __forceinline__ void gemm_phase(PG8_LAS unsigned char* lds, const Gemm g, const Sched& S, const Epi& E) {
;     ...
;     PG8_RTAB(cur, 0);
;     ...
;         PG8_STAGE(PG8_SB(0, 0), cB, voffB); PG8_STAGE(PG8_SA(0, 0), cA, voffA); PG8_STAGE(PG8_SB(0, 1), cB + hstep, voffB); PG8_STAGE(PG8_SA(0, 1), cA + hstep, voffA);
;         if (wr == 1) PG8_BAR;
.LBB0_1082:
	s_andn2_b64 vcc, exec, s[2:3]
	s_cbranch_vccnz .LBB0_1170
	s_movk_i32 s2, 0x100
	v_cmp_gt_u32_e64 s[2:3], s2, v208
	s_add_u32 s18, s28, 0xe00000
	s_addc_u32 s19, s29, 0
	s_lshr_b32 s5, s39, 6
	s_ashr_i32 s69, s68, 31
	s_ashr_i32 s7, s6, 31
	s_lshr_b32 s4, s39, 8
	s_lshl_b32 s21, s5, 10
	s_lshl_b64 s[24:25], s[68:69], 19
	s_lshl_b64 s[12:13], s[6:7], 19
	s_add_u32 s72, s18, s12
	v_mov_b32_e32 v143, 0
	v_lshlrev_b32_e32 v140, 4, v208
	s_addc_u32 s73, s19, s13
	s_add_i32 s22, s21, 0
	v_mov_b32_e32 v141, v143
	s_add_i32 m0, s22, 0x10000
	s_waitcnt lgkmcnt(0)
	v_lshl_add_u64 v[0:1], s[72:73], 0, v[140:141]
	s_mov_b64 s[12:13], 0x2000
	global_load_lds_dwordx4 v140, s[72:73]
	v_lshl_add_u64 v[2:3], v[0:1], 0, s[12:13]
	s_add_i32 m0, s22, 0x12000
	s_mov_b64 s[14:15], 0x40000
	global_load_lds_dwordx4 v[2:3], off
	s_add_i32 m0, s22, 0x14000
	v_lshl_add_u64 v[2:3], v[0:1], 0, s[14:15]
	global_load_lds_dwordx4 v[2:3], off
	s_add_i32 m0, s22, 0x16000
	s_mov_b64 s[16:17], 0x42000
	s_add_u32 s70, s8, s24
	v_lshl_add_u64 v[2:3], v[0:1], 0, s[16:17]
	s_addc_u32 s71, s9, s25
	global_load_lds_dwordx4 v[2:3], off
	v_lshl_add_u64 v[2:3], s[70:71], 0, v[140:141]
	s_mov_b32 m0, s22
	s_add_i32 s23, s22, 0x2000
	global_load_lds_dwordx4 v140, s[70:71]
	v_lshl_add_u64 v[4:5], v[2:3], 0, s[12:13]
	s_mov_b32 m0, s23
	s_add_i32 s30, s22, 0x4000
	global_load_lds_dwordx4 v[4:5], off
	v_lshl_add_u64 v[4:5], v[2:3], 0, s[14:15]
	s_mov_b32 m0, s30
	s_add_i32 s31, s22, 0x6000
	global_load_lds_dwordx4 v[4:5], off
	v_lshl_add_u64 v[4:5], v[2:3], 0, s[16:17]
	s_mov_b32 m0, s31
	s_cmp_eq_u32 s4, 1
	global_load_lds_dwordx4 v[4:5], off
	s_cselect_b64 s[24:25], -1, 0
	s_and_saveexec_b64 s[98:99], s[2:3]
	s_cbranch_execz .LBB0_1085
	v_lshl_or_b32 v224, s68, 8, v208
	s_waitcnt lgkmcnt(0)
	v_ashrrev_i32_e32 v225, 31, v224
	v_lshlrev_b64 v[224:225], 6, v[224:225]
	v_lshl_add_u64 v[240:241], s[10:11], 0, v[224:225]
	global_load_dwordx4 v[224:227], v[240:241], off
	global_load_dwordx4 v[228:231], v[240:241], off offset:16
	global_load_dwordx4 v[232:235], v[240:241], off offset:32
	global_load_dwordx4 v[236:239], v[240:241], off offset:48
	s_waitcnt vmcnt(0)
	v_pk_add_f32 v[226:227], v[226:227], v[230:231]
	v_pk_add_f32 v[224:225], v[224:225], v[228:229]
	v_pk_add_f32 v[228:229], v[234:235], v[238:239]
	v_pk_add_f32 v[230:231], v[232:233], v[236:237]
	v_pk_add_f32 v[226:227], v[226:227], v[228:229]
	v_pk_add_f32 v[224:225], v[224:225], v[230:231]
	s_nop 0
	v_pk_mov_b32 v[228:229], v[224:225], v[226:227] op_sel:[1,0]
	v_mov_b32_e32 v225, v227
	v_pk_add_f32 v[224:225], v[228:229], v[224:225]
	s_nop 0
	v_add_f32_e32 v224, v224, v225
	v_mov_b32_e32 v225, 0x358637bd
	v_fmac_f32_e32 v225, 0x3a800000, v224
	v_rsq_f32_e32 v224, v225
	v_lshl_add_u32 v225, v208, 2, 0
	v_add_u32_e32 v225, 0x20400, v225
	ds_write_b32 v225, v224
.LBB0_1085:
	s_or_b64 exec, exec, s[98:99]
	s_cmp_lg_u32 s4, 1
	s_mov_b32 s7, 0
	s_cbranch_scc1 .LBB0_1087
	s_barrier

; #define PG8_STAGE(bufoff, gbase, voff) do { _Pragma("unroll") for (int _i = 0; _i < 2; ++_i) \
;         __builtin_amdgcn_global_load_lds((const unsigned*)((const char*)(gbase) + (voff)[_i]), (PG8_LAS unsigned*)(lds + (bufoff) + ldsw + _i * 8192), 16, 0, 0); } while (0)
; #define PG8_BAR __builtin_amdgcn_s_barrier()
; template <class Epi, class Sched, bool ALIGN_EPI = false, bool SP2 = false, bool TA = true>
; __device__ __forceinline__ void gemm_phase(PG8_LAS unsigned char* lds, const Gemm g, const Sched& S, const Epi& E) {
;     ...
;     PG8_RTAB(cur, 0);
;     ...
;         PG8_STAGE(PG8_SB(0, 0), cB, voffB); PG8_STAGE(PG8_SA(0, 0), cA, voffA); PG8_STAGE(PG8_SB(0, 1), cB + hstep, voffB); PG8_STAGE(PG8_SA(0, 1), cA + hstep, voffA);
;         if (wr == 1) PG8_BAR;
.LBB0_1613:
	s_cmp_lt_i32 s36, 12
	s_cselect_b64 s[0:1], -1, 0
	s_and_b64 s[0:1], s[0:1], s[2:3]
	s_andn2_b64 vcc, exec, s[0:1]
	s_cbranch_vccnz .LBB0_1634
	s_cmpk_gt_i32 s20, 0xaff
	v_readfirstlane_b32 s44, v208
	s_cbranch_scc1 .LBB0_1634
	s_ashr_i32 s18, s20, 31
	s_lshr_b32 s2, s18, 29
	s_add_i32 s2, s20, s2
	s_ashr_i32 s3, s2, 3
	s_and_b32 s2, s2, -8
	s_sub_i32 s2, s20, s2
	s_cmp_lt_i32 s2, 0
	s_movk_i32 s4, 0x161
	s_cselect_b32 s4, s4, 0x160
	s_mul_i32 s2, s2, s4
	s_add_i32 s2, s2, s3
	s_mul_hi_i32 s3, s2, 0x2e8ba2e9
	s_lshr_b32 s4, s3, 31
	s_ashr_i32 s3, s3, 5
	s_add_i32 s3, s3, s4
	s_lshl_b32 s4, s3, 3
	s_mulk_i32 s3, 0xb0
	s_sub_i32 s2, s2, s3
	s_sext_i32_i16 s3, s2
	s_bfe_u32 s3, s3, 0x3001c
	s_add_i32 s3, s2, s3
	s_sext_i32_i16 s5, s3
	s_and_b32 s3, s3, 0xfff8
	s_sub_i32 s2, s2, s3
	s_sext_i32_i16 s2, s2
	s_add_i32 s52, s4, s2
	s_movk_i32 s2, 0x100
	s_lshr_b32 s6, s5, 3
	v_cmp_gt_u32_e64 s[2:3], s2, v208
	s_sext_i32_i16 s54, s6
	s_add_u32 s19, s28, 0x2100000
	s_addc_u32 s21, s29, 0
	s_lshr_b32 s5, s44, 6
	s_ashr_i32 s53, s52, 31
	s_ashr_i32 s55, s54, 31
	s_lshr_b32 s4, s44, 8
	s_lshl_b32 s22, s5, 10
	s_lshl_b64 s[16:17], s[52:53], 19
	s_lshl_b64 s[6:7], s[54:55], 19
	s_add_u32 s58, s19, s6
	v_mov_b32_e32 v131, 0
	v_lshlrev_b32_e32 v128, 4, v208
	s_addc_u32 s59, s21, s7
	s_add_i32 s23, s22, 0
	v_mov_b32_e32 v129, v131
	s_add_i32 m0, s23, 0x10000
	s_waitcnt lgkmcnt(0)
	v_lshl_add_u64 v[0:1], s[58:59], 0, v[128:129]
	s_mov_b64 s[6:7], 0x2000
	global_load_lds_dwordx4 v128, s[58:59]
	v_lshl_add_u64 v[2:3], v[0:1], 0, s[6:7]
	s_add_i32 m0, s23, 0x12000
	s_mov_b64 s[12:13], 0x40000
	global_load_lds_dwordx4 v[2:3], off
	s_add_i32 m0, s23, 0x14000
	v_lshl_add_u64 v[2:3], v[0:1], 0, s[12:13]
	global_load_lds_dwordx4 v[2:3], off
	s_add_i32 m0, s23, 0x16000
	s_mov_b64 s[14:15], 0x42000
	s_add_u32 s56, s8, s16
	v_lshl_add_u64 v[2:3], v[0:1], 0, s[14:15]
	s_addc_u32 s57, s9, s17
	global_load_lds_dwordx4 v[2:3], off
	v_lshl_add_u64 v[2:3], s[56:57], 0, v[128:129]
	s_mov_b32 m0, s23
	s_add_i32 s30, s23, 0x2000
	global_load_lds_dwordx4 v128, s[56:57]
	v_lshl_add_u64 v[4:5], v[2:3], 0, s[6:7]
	s_mov_b32 m0, s30
	s_add_i32 s31, s23, 0x4000
	global_load_lds_dwordx4 v[4:5], off
	v_lshl_add_u64 v[4:5], v[2:3], 0, s[12:13]
	s_mov_b32 m0, s31
	s_add_i32 s33, s23, 0x6000
	global_load_lds_dwordx4 v[4:5], off
	v_lshl_add_u64 v[4:5], v[2:3], 0, s[14:15]
	s_mov_b32 m0, s33
	s_cmp_eq_u32 s4, 1
	global_load_lds_dwordx4 v[4:5], off
	s_cselect_b64 s[16:17], -1, 0
	s_and_saveexec_b64 s[98:99], s[2:3]
	s_cbranch_execz .LBB0_1617
	v_lshl_or_b32 v224, s52, 8, v208
	s_waitcnt lgkmcnt(0)
	v_ashrrev_i32_e32 v225, 31, v224
	v_lshlrev_b64 v[224:225], 6, v[224:225]
	v_lshl_add_u64 v[240:241], s[10:11], 0, v[224:225]
	global_load_dwordx4 v[224:227], v[240:241], off
	global_load_dwordx4 v[228:231], v[240:241], off offset:16
	global_load_dwordx4 v[232:235], v[240:241], off offset:32
	global_load_dwordx4 v[236:239], v[240:241], off offset:48
	s_waitcnt vmcnt(0)
	v_pk_add_f32 v[226:227], v[226:227], v[230:231]
	v_pk_add_f32 v[224:225], v[224:225], v[228:229]
	v_pk_add_f32 v[228:229], v[234:235], v[238:239]
	v_pk_add_f32 v[230:231], v[232:233], v[236:237]
	v_pk_add_f32 v[226:227], v[226:227], v[228:229]
	v_pk_add_f32 v[224:225], v[224:225], v[230:231]
	s_nop 0
	v_pk_mov_b32 v[228:229], v[224:225], v[226:227] op_sel:[1,0]
	v_mov_b32_e32 v225, v227
	v_pk_add_f32 v[224:225], v[228:229], v[224:225]
	s_nop 0
	v_add_f32_e32 v224, v224, v225
	v_mov_b32_e32 v225, 0x358637bd
	v_fmac_f32_e32 v225, 0x3a800000, v224
	v_rsq_f32_e32 v224, v225
	v_lshl_add_u32 v225, v208, 2, 0
	v_add_u32_e32 v225, 0x20400, v225
	ds_write_b32 v225, v224

; #define PG8_STAGE(bufoff, gbase, voff) do { _Pragma("unroll") for (int _i = 0; _i < 2; ++_i) \
;         __builtin_amdgcn_global_load_lds((const unsigned*)((const char*)(gbase) + (voff)[_i]), (PG8_LAS unsigned*)(lds + (bufoff) + ldsw + _i * 8192), 16, 0, 0); } while (0)
; #define PG8_BAR __builtin_amdgcn_s_barrier()
; template <class Epi, class Sched, bool ALIGN_EPI = false, bool SP2 = false, bool TA = true>
; __device__ __forceinline__ void gemm_phase(PG8_LAS unsigned char* lds, const Gemm g, const Sched& S, const Epi& E) {
;     ...
;     PG8_RTAB(cur, 0);
;     ...
;         PG8_STAGE(PG8_SB(0, 0), cB, voffB); PG8_STAGE(PG8_SA(0, 0), cA, voffA); PG8_STAGE(PG8_SB(0, 1), cB + hstep, voffB); PG8_STAGE(PG8_SA(0, 1), cA + hstep, voffA);
;         if (wr == 1) PG8_BAR;
.LBB0_1819:
	s_add_i32 s0, s3, s0
	s_ashr_i32 s1, s0, 31
	s_lshr_b32 s1, s1, 27
	s_add_i32 s1, s0, s1
	s_ashr_i32 s2, s1, 5
	s_and_b32 s1, s1, 0xffe0
	s_sub_i32 s0, s0, s1
	s_bfe_i32 s1, s0, 0x80000
	s_bfe_u32 s1, s1, 0x3000c
	s_add_i32 s1, s0, s1
	s_bfe_i32 s3, s1, 0x80000
	s_and_b32 s1, s1, 0xf8
	s_sub_i32 s0, s0, s1
	s_lshl_b32 s2, s2, 3
	s_sext_i32_i8 s0, s0
	s_sext_i32_i16 s3, s3
	s_add_i32 s44, s2, s0
	s_movk_i32 s0, 0x100
	s_lshr_b32 s35, s3, 3
	v_cmp_gt_u32_e64 s[0:1], s0, v208
	v_mov_b32_e32 v0, s35
	s_add_u32 s22, s28, 0x3a00000
	v_readfirstlane_b32 s46, v0
	s_mov_b32 s47, 0
	s_addc_u32 s23, s29, 0
	s_lshr_b32 s3, s34, 6
	s_ashr_i32 s45, s44, 31
	s_bfe_i64 s[4:5], s[46:47], 0x80000
	s_lshr_b32 s2, s34, 8
	s_lshl_b32 s33, s3, 10
	s_lshl_b64 s[14:15], s[44:45], 19
	s_lshl_b64 s[4:5], s[4:5], 19
	v_mov_b32_e32 v147, 0
	s_add_u32 s50, s22, s4
	v_lshlrev_b32_e32 v144, 4, v208
	s_addc_u32 s51, s23, s5
	s_add_i32 s52, s33, 0
	v_mov_b32_e32 v145, v147
	s_add_i32 m0, s52, 0x10000
	s_waitcnt lgkmcnt(0)
	v_lshl_add_u64 v[0:1], s[50:51], 0, v[144:145]
	s_mov_b64 s[4:5], 0x2000
	global_load_lds_dwordx4 v144, s[50:51]
	v_lshl_add_u64 v[2:3], v[0:1], 0, s[4:5]
	s_add_i32 m0, s52, 0x12000
	s_mov_b64 s[6:7], 0x40000
	global_load_lds_dwordx4 v[2:3], off
	s_add_i32 m0, s52, 0x14000
	v_lshl_add_u64 v[2:3], v[0:1], 0, s[6:7]
	global_load_lds_dwordx4 v[2:3], off
	s_add_i32 m0, s52, 0x16000
	s_mov_b64 s[12:13], 0x42000
	s_add_u32 s48, s8, s14
	v_lshl_add_u64 v[2:3], v[0:1], 0, s[12:13]
	s_addc_u32 s49, s9, s15
	s_add_i32 s53, s52, 0x2000
	global_load_lds_dwordx4 v[2:3], off
	s_mov_b32 m0, s52
	s_add_u32 s14, s48, 0x40000
	v_add_u32_e32 v146, 0x2000, v144
	global_load_lds_dwordx4 v144, s[48:49]
	s_mov_b32 m0, s53
	s_addc_u32 s15, s49, 0
	s_add_i32 s54, s52, 0x4000
	global_load_lds_dwordx4 v146, s[48:49]
	s_mov_b32 m0, s54
	s_add_i32 s55, s52, 0x6000
	global_load_lds_dwordx4 v144, s[14:15]
	s_mov_b32 m0, s55
	s_cmp_eq_u32 s2, 1
	global_load_lds_dwordx4 v146, s[14:15]
	s_cselect_b64 s[14:15], -1, 0
	s_and_saveexec_b64 s[98:99], s[0:1]
	s_cbranch_execz .LBB0_1821
	v_lshl_or_b32 v224, s44, 8, v208
	s_waitcnt lgkmcnt(0)
	v_ashrrev_i32_e32 v225, 31, v224
	v_lshlrev_b64 v[224:225], 6, v[224:225]
	v_lshl_add_u64 v[240:241], s[10:11], 0, v[224:225]
	global_load_dwordx4 v[224:227], v[240:241], off
	global_load_dwordx4 v[228:231], v[240:241], off offset:16
	global_load_dwordx4 v[232:235], v[240:241], off offset:32
	global_load_dwordx4 v[236:239], v[240:241], off offset:48
	s_waitcnt vmcnt(0)
	v_pk_add_f32 v[226:227], v[226:227], v[230:231]
	v_pk_add_f32 v[224:225], v[224:225], v[228:229]
	v_pk_add_f32 v[228:229], v[234:235], v[238:239]
	v_pk_add_f32 v[230:231], v[232:233], v[236:237]
	v_pk_add_f32 v[226:227], v[226:227], v[228:229]
	v_pk_add_f32 v[224:225], v[224:225], v[230:231]
	s_nop 0
	v_pk_mov_b32 v[228:229], v[224:225], v[226:227] op_sel:[1,0]
	v_mov_b32_e32 v225, v227
	v_pk_add_f32 v[224:225], v[228:229], v[224:225]
	s_nop 0
	v_add_f32_e32 v224, v224, v225
	v_mov_b32_e32 v225, 0x358637bd
	v_fmac_f32_e32 v225, 0x3a800000, v224
	v_rsq_f32_e32 v224, v225
	v_lshl_add_u32 v225, v208, 2, 0
	v_add_u32_e32 v225, 0x20400, v225
	ds_write_b32 v225, v224
.LBB0_1821:
	s_or_b64 exec, exec, s[98:99]
	s_cmp_lg_u32 s2, 1
	s_cbranch_scc1 .LBB0_1823
	s_barrier
